# HGRN scan: prefetch loads and output stores via precomputed per-lane offsets + scalar bases
# speedup vs baseline: 1.0137x; 1.0003x over previous
.LBB0_499:
	s_lshl_b32 s14, s4, 1
	s_or_b32 s14, s14, s11
	s_ashr_i32 s15, s14, 31
	s_lshl_b64 s[14:15], s[14:15], 18
	s_add_u32 s11, s72, s14
	s_addc_u32 s14, s73, s15
	s_lshl_b32 s13, s13, 2
	s_add_u32 s11, s11, s13
	s_addc_u32 s13, s14, 0
	s_lshl_b32 s14, s8, 6
	s_add_u32 s14, s11, s14
	s_addc_u32 s15, s13, 0
	v_lshlrev_b32_e32 v0, 2, v58
	v_lshl_add_u64 v[30:31], s[14:15], 0, v[0:1]
	s_and_b64 s[14:15], exec, s[2:3]
	s_mov_b32 s29, 0
	s_cselect_b32 s28, 0, 0x3f000
	v_lshl_add_u64 v[10:11], v[30:31], 0, s[28:29]
	global_load_dwordx4 v[10:13], v[10:11], off
	s_lshr_b32 s13, s10, 7
	s_lshl_b32 s14, s12, 1
	s_lshl_b32 s38, s13, 4
	s_lshl_b64 s[48:49], s[4:5], 24
	s_cmp_le_u32 s14, s13
	s_cselect_b64 s[30:31], -1, 0
	s_lshl_b32 s39, s12, 5
	s_lshl_b32 s28, s12, 6
	s_or_b32 s40, s14, 1
	v_xor_b32_e32 v0, s8, v63
	s_cmp_lt_u32 s14, s13
	v_lshl_add_u32 v70, v0, 4, v90
	v_xor_b32_e32 v0, v16, v63
	v_lshl_or_b32 v16, s12, 4, v50
	s_cselect_b64 s[34:35], -1, 0
	s_lshl_b32 s12, s40, 4
	s_lshl_b32 s47, s40, 5
	s_and_b64 s[50:51], exec, s[2:3]
	s_cselect_b32 s41, s76, s36
	s_cselect_b32 s40, s77, s33
	s_add_u32 s41, s41, s48
	v_mov_b32_e32 v15, v1
	s_waitcnt vmcnt(22)
	v_or_b32_e32 v18, s39, v50
	s_addc_u32 s40, s40, s49
	v_lshl_add_u32 v71, v0, 4, v92
	v_lshl_add_u64 v[32:33], s[6:7], 0, v[14:15]
	v_or_b32_e32 v0, s38, v50
	s_movk_i32 s6, 0x110
	v_mul_u32_u24_e32 v17, 0x110, v16
	v_mad_u32_u24 v114, v16, s37, 0
	v_lshl_or_b32 v16, s8, 4, v50
	v_mul_u32_u24_e32 v19, 0x110, v18
	v_or_b32_e32 v18, s39, v58
	s_add_u32 s20, s41, s20
	v_mul_lo_u32 v15, v0, s6
	v_mul_lo_u32 v16, v16, s37
	v_cmp_gt_u32_e64 s[4:5], v18, v0
	v_cmp_lt_u32_e64 s[6:7], v18, v0
	v_or_b32_e32 v20, 2, v18
	v_or_b32_e32 v18, 3, v18
	s_addc_u32 s40, s40, 0
	v_add_u32_e32 v115, 0, v16
	v_lshl_add_u32 v16, s8, 5, v94
	s_mulk_i32 s8, 0x880
	s_mulk_i32 s9, 0x110
	v_cmp_gt_u32_e64 s[10:11], v18, v0
	v_or_b32_e32 v18, s12, v50
	s_add_u32 s20, s20, s21
	v_add_u32_e32 v116, s8, v89
	v_add_u32_e32 v117, s9, v89
	v_cmp_gt_u32_e64 s[8:9], v20, v0
	v_mul_u32_u24_e32 v20, 0x110, v18
	v_or_b32_e32 v18, s12, v58
	s_addc_u32 s21, s40, 0
	v_cmp_gt_u32_e64 s[12:13], v18, v0
	v_cmp_lt_u32_e64 s[14:15], v18, v0
	v_or_b32_e32 v21, 2, v18
	v_or_b32_e32 v18, 3, v18
	s_add_u32 s20, s20, s39
	v_mul_lo_u32 v14, v0, s37
	v_cmp_gt_u32_e64 s[16:17], v21, v0
	v_cmp_gt_u32_e64 s[18:19], v18, v0
	s_addc_u32 s21, s21, 0
	v_lshlrev_b32_e32 v0, 1, v50
	v_mov_b32_e32 v18, 0
	s_mov_b32 s46, 1
	v_add_u32_e32 v113, v91, v14
	v_lshl_add_u64 v[34:35], s[20:21], 0, v[0:1]
	v_subrev_u32_e32 v0, s39, v106
	s_sub_i32 s48, 0, s25
	v_or_b32_e32 v118, s38, v58
	v_subrev_u32_e32 v119, s38, v104
	v_or_b32_e32 v120, s39, v74
	s_mov_b32 s49, 62
	v_add_u32_e32 v121, v99, v19
	v_add_u32_e32 v122, v99, v20
	v_add_u32_e32 v123, v100, v17
	v_add_u32_e32 v124, v93, v14
	v_add_u32_e32 v125, v16, v96
	v_add_u32_e32 v126, v99, v15
	s_mov_b32 s50, s29
	v_mov_b32_e32 v19, v18
	v_mov_b32_e32 v20, v18
	v_mov_b32_e32 v21, v18
	v_mov_b32_e32 v14, v18
	v_mov_b32_e32 v15, v18
	v_mov_b32_e32 v16, v18
	v_mov_b32_e32 v17, v18
	s_and_b64 s[94:95], s[2:3], exec
	s_cselect_b32 s93, 0, -1
	v_readfirstlane_b32 s54, v26
	v_readfirstlane_b32 s55, v27
	v_readfirstlane_b32 s56, v28
	v_readfirstlane_b32 s57, v29
	v_readfirstlane_b32 s58, v32
	v_readfirstlane_b32 s59, v33
	v_readfirstlane_b32 s60, v34
	v_readfirstlane_b32 s61, v35
	s_lshl_b32 s94, s24, 1
	s_add_i32 s95, s25, 64
	s_sub_i32 s96, 0xfb8, s25
	s_cmp_eq_u32 s93, 0
	s_cselect_b32 s95, s95, s96
	s_mul_i32 s96, s95, s94
	s_add_u32 s54, s54, s96
	s_addc_u32 s55, s55, 0
	s_mul_i32 s96, s95, 0x4800
	s_add_u32 s56, s56, s96
	s_addc_u32 s57, s57, 0
	s_cmp_eq_u32 s93, 0
	s_cselect_b32 s95, 64, 0xf80
	s_mul_i32 s96, s95, 0x4800
	s_add_u32 s58, s58, s96
	s_addc_u32 s59, s59, 0
	s_and_b32 s96, s93, 0xfc0000
	s_add_u32 s60, s60, s96
	s_addc_u32 s61, s61, 0
	s_lshl_b32 s62, s94, 6
	s_xor_b32 s62, s62, s93
	s_sub_i32 s62, s62, s93
	s_xor_b32 s63, s93, 0x120000
	s_sub_i32 s63, s63, s93
	s_xor_b32 s92, s93, 0x40000
	s_sub_i32 s92, s92, s93
	v_lshlrev_b32_e32 v140, 2, v220
	s_mul_i32 s95, s94, 7
	s_and_b32 s95, s95, s93
	v_add_u32_e32 v140, s95, v140
	s_xor_b32 s95, s94, s93
	s_sub_i32 s95, s95, s93
	v_add_u32_e32 v141, s95, v140
	v_add_u32_e32 v142, s95, v141
	v_add_u32_e32 v143, s95, v142
	v_add_u32_e32 v144, s95, v143
	v_add_u32_e32 v145, s95, v144
	v_add_u32_e32 v146, s95, v145
	v_add_u32_e32 v147, s95, v146
	v_lshlrev_b32_e32 v148, 2, v220
	s_and_b32 s95, s93, 0x1f800
	v_add_u32_e32 v148, s95, v148
	s_xor_b32 s95, s93, 0x4800
	s_sub_i32 s95, s95, s93
	v_add_u32_e32 v149, s95, v148
	v_add_u32_e32 v150, s95, v149
	v_add_u32_e32 v151, s95, v150
	v_add_u32_e32 v152, s95, v151
	v_add_u32_e32 v153, s95, v152
	v_add_u32_e32 v154, s95, v153
	v_add_u32_e32 v155, s95, v154
	s_and_b32 s96, s93, 64
	v_xor_b32_e32 v156, s93, v120
	v_add_u32_e32 v156, s96, v156
	v_mul_u32_u24_e32 v156, 0x4800, v156
	v_lshl_add_u32 v156, v50, 2, v156
	v_add_u32_e32 v157, s95, v156
	v_add_u32_e32 v158, s95, v157
	v_add_u32_e32 v159, s95, v158
	v_add_u32_e32 v160, s95, v159
	v_add_u32_e32 v161, s95, v160
	v_add_u32_e32 v162, s95, v161
	v_add_u32_e32 v163, s95, v162
	v_xor_b32_e32 v164, s93, v118
	v_add_u32_e32 v164, s96, v164
	v_lshlrev_b32_e32 v164, 12, v164
	v_lshl_add_u32 v164, v50, 1, v164
	s_xor_b32 s95, s93, 0x1000
	s_sub_i32 s95, s95, s93
	v_add_u32_e32 v165, s95, v164
	v_add_u32_e32 v166, s95, v165
	v_add_u32_e32 v167, s95, v166
	s_branch .LBB0_501
.LBB0_500:
	s_nop 0
	v_add_u32_e32 v38, s47, v113
	ds_write_b64 v38, v[36:37] offset:57856
	ds_read_b128 v[36:39], v126
	ds_read_b128 v[128:131], v123
	v_add_u32_e32 v127, v114, v81
	s_waitcnt vmcnt(17)
	v_pk_mul_f32 v[20:21], v[12:13], v[20:21]
	v_pk_mul_f32 v[18:19], v[10:11], v[18:19]
	v_pk_mul_f32 v[12:13], v[12:13], v[16:17]
	s_waitcnt lgkmcnt(0)
	v_mfma_f32_16x16x32_bf16 v[36:39], v[36:39], v[128:131], 0
	ds_read_b128 v[128:131], v126 offset:64
	ds_read_b128 v[132:135], v123 offset:64
	v_pk_mul_f32 v[10:11], v[10:11], v[14:15]
	s_add_i32 s49, s49, -1
	s_add_i32 s46, s46, 1
	s_waitcnt lgkmcnt(0)
	v_mfma_f32_16x16x32_bf16 v[36:39], v[128:131], v[132:135], v[36:39]
	ds_read_b128 v[128:131], v126 offset:128
	ds_read_b128 v[132:135], v123 offset:128
	s_waitcnt lgkmcnt(0)
	v_mfma_f32_16x16x32_bf16 v[36:39], v[128:131], v[132:135], v[36:39]
	ds_read_b128 v[128:131], v126 offset:192
	ds_read_b128 v[132:135], v123 offset:192
	s_waitcnt lgkmcnt(0)
	s_barrier
	s_waitcnt lgkmcnt(0)
	v_mfma_f32_16x16x32_bf16 v[36:39], v[128:131], v[132:135], v[36:39]
	ds_read_b128 v[128:131], v124 offset:57856
	ds_read_b128 v[132:135], v127 offset:53248
	v_add_u32_e32 v127, v114, v82
	s_waitcnt lgkmcnt(0)
	v_mfma_f32_16x16x32_bf16 v[36:39], v[128:131], v[132:135], v[36:39]
	ds_read_b128 v[128:131], v124 offset:57920
	ds_read_b128 v[132:135], v127 offset:53248
	s_add_i32 s29, s29, 64
	s_waitcnt lgkmcnt(0)
	v_mfma_f32_16x16x32_bf16 v[36:39], v[128:131], v[132:135], v[36:39]
	s_nop 7
	v_cvt_pk_bf16_f32 v128, v36, s0
	v_cvt_pk_bf16_f32 v129, v37, s0
	v_cvt_pk_bf16_f32 v130, v38, s0
	v_cvt_pk_bf16_f32 v131, v39, s0
	global_store_short v164, v128, s[60:61]
	global_store_short v165, v129, s[60:61]
	global_store_short v166, v130, s[60:61]
	global_store_short v167, v131, s[60:61]
	s_add_u32 s60, s60, s92
	s_addc_u32 s61, s61, s93
	v_add_u32_e32 v127, v115, v81
	ds_read_b128 v[36:39], v127 offset:34816
	v_add_u32_e32 v132, v95, v81
	ds_read_b128 v[128:131], v132 offset:53248
	v_add_u32_e32 v133, v115, v82
	s_waitcnt lgkmcnt(0)
	v_mfma_f32_16x16x32_bf16 v[18:21], v[36:39], v[128:131], v[18:21]
	ds_read_b128 v[36:39], v133 offset:34816
	v_add_u32_e32 v134, v95, v82
	ds_read_b128 v[128:131], v134 offset:53248
	s_waitcnt lgkmcnt(0)
	v_mfma_f32_16x16x32_bf16 v[18:21], v[36:39], v[128:131], v[18:21]
	s_sub_i32 s50, s50, 64
	s_cmpk_eq_i32 s50, 0xf000
	s_waitcnt vmcnt(4)
	s_nop 4
	v_pk_mul_f32 v[36:37], v[24:25], v[20:21]
	v_pk_mul_f32 v[38:39], v[22:23], v[18:19]
	s_nop 0
	v_cvt_pk_bf16_f32 v38, v38, v39
	v_cvt_pk_bf16_f32 v39, v36, v37
	ds_write_b64 v125, v[38:39]
	ds_read_b128 v[14:17], v127 offset:34816
	ds_read_b128 v[36:39], v132 offset:55552
	s_waitcnt lgkmcnt(0)
	v_mfma_f32_16x16x32_bf16 v[10:13], v[14:17], v[36:39], v[10:13]
	ds_read_b128 v[14:17], v133 offset:34816
	ds_read_b128 v[36:39], v134 offset:55552
	s_waitcnt lgkmcnt(0)
	v_mfma_f32_16x16x32_bf16 v[14:17], v[14:17], v[36:39], v[10:13]
	s_nop 7
	v_pk_mul_f32 v[10:11], v[24:25], v[16:17]
	v_pk_mul_f32 v[12:13], v[22:23], v[14:15]
	s_nop 0
	v_cvt_pk_bf16_f32 v12, v12, v13
	v_cvt_pk_bf16_f32 v13, v10, v11
	ds_write_b64 v125, v[12:13] offset:4352
	s_waitcnt lgkmcnt(0)
	s_barrier
	v_mov_b64_e32 v[10:11], v[22:23]
	v_mov_b64_e32 v[12:13], v[24:25]
	s_cbranch_scc1 .LBB0_436

.LBB0_503:
	s_waitcnt lgkmcnt(0)
	s_barrier
	s_cmpk_eq_i32 s50, 0xf040
	s_cbranch_scc1 .LBB0_507
	global_load_dword v40, v140, s[54:55]
	global_load_dword v41, v148, s[56:57]
	global_load_dword v42, v141, s[54:55]
	global_load_dword v43, v149, s[56:57]
	global_load_dword v44, v142, s[54:55]
	global_load_dword v45, v150, s[56:57]
	global_load_dword v46, v143, s[54:55]
	global_load_dword v47, v151, s[56:57]
	global_load_dword v48, v144, s[54:55]
	global_load_dword v49, v152, s[56:57]
	global_load_dword v64, v145, s[54:55]
	global_load_dword v65, v153, s[56:57]
	global_load_dword v66, v146, s[54:55]
	global_load_dword v67, v154, s[56:57]
	global_load_dword v68, v147, s[54:55]
	global_load_dword v69, v155, s[56:57]
	s_add_u32 s54, s54, s62
	s_addc_u32 s55, s55, s93
	s_add_u32 s56, s56, s63
	s_addc_u32 s57, s57, s93
	s_and_b64 vcc, exec, s[20:21]
	s_cbranch_vccnz .LBB0_506
	global_load_dword v2, v156, s[58:59] offset:2048 nt
	global_load_dword v3, v157, s[58:59] offset:2048 nt
	global_load_dword v4, v158, s[58:59] offset:2048 nt
	global_load_dword v5, v159, s[58:59] offset:2048 nt
	global_load_dword v6, v160, s[58:59] offset:2048 nt
	global_load_dword v7, v161, s[58:59] offset:2048 nt
	global_load_dword v8, v162, s[58:59] offset:2048 nt
	global_load_dword v9, v163, s[58:59] offset:2048 nt
	s_add_u32 s58, s58, s63
	s_addc_u32 s59, s59, s93
